# prep: x_prompt f32->bf16 copy hand-written with 16 loads in flight per thread (compiled loop had 4)
# speedup vs baseline: 1.0071x; 1.0041x over previous
; __device__ __forceinline__ void cvt_rows(const float* __restrict__ src, bf16_t* __restrict__ dst, size_t n4, size_t gtid, size_t gn) {
;   for (size_t i0 = gtid; i0 < n4; i0 += 4 * gn) {
;     f32x4 v[4];
; #pragma unroll
;     for (int q = 0; q < 4; ++q) { const size_t i = i0 + q * gn; v[q] = i < n4 ? *(const f32x4*)(src + i * 4) : (f32x4){0.f, 0.f, 0.f, 0.f}; }
; #pragma unroll
;     for (int q = 0; q < 4; ++q) {
;       const size_t i = i0 + q * gn;
;       if (i < n4) { u32x2 w; w[0] = cvt_pk_bf16(v[q][0], v[q][1]); w[1] = cvt_pk_bf16(v[q][2], v[q][3]); *(u32x2*)(dst + i * 4) = w; }
;     }
;   }
; }
; __device__ __forceinline__ void phase_prep(KP kp, unsigned char* shm) {
;     ...
;   cvt_rows(kp->x_prompt, (bf16_t*)(ws + W_XBF), (size_t)MP * 256, gtid, gn);
.LBB0_2220:
	s_ashr_i32 s83, s82, 31
	v_writelane_b32 v254, s82, 6
	s_lshl_b64 s[6:7], s[82:83], 9
	v_ashrrev_i32_e32 v35, 31, v34
	v_writelane_b32 v254, s83, 7
	v_lshl_add_u64 v[36:37], s[6:7], 0, v[34:35]
	v_readlane_b32 s0, v254, 0
	v_readlane_b32 s1, v254, 1
	s_ashr_i32 s1, s0, 31
	s_lshl_b64 s[8:9], s[0:1], 9
	s_mov_b64 s[4:5], 0x800000
	s_mul_hi_i32 s11, s0, 0x600
	s_mul_i32 s10, s0, 0x600
	s_mul_hi_i32 s33, s0, 0x6000
	v_writelane_b32 v254, s0, 8
	v_cmp_gt_u64_e32 vcc, s[4:5], v[36:37]
	s_mul_i32 s49, s0, 0x6000
	v_writelane_b32 v254, s1, 9
	s_and_saveexec_b64 s[12:13], vcc
	s_cbranch_execz .LBB0_2235
	s_cmp_lg_u32 s8, 0x20000
	s_cbranch_scc1 .Lprepx_orig
	s_cmp_lg_u32 s9, 0
	s_cbranch_scc1 .Lprepx_orig
	s_load_dwordx2 s[14:15], s[20:21], 0x0
	s_load_dwordx2 s[24:25], s[20:21], 0xb0
	v_lshlrev_b32_e32 v2, 4, v36
	v_lshlrev_b32_e32 v3, 3, v36
	s_waitcnt lgkmcnt(0)
	s_add_u32 s24, s24, 0x39c0000
	s_addc_u32 s25, s25, 0
	global_load_dwordx4 v[64:67], v2, s[14:15]
	s_add_u32 s14, s14, 0x200000
	s_addc_u32 s15, s15, 0
	global_load_dwordx4 v[68:71], v2, s[14:15]
	s_add_u32 s14, s14, 0x200000
	s_addc_u32 s15, s15, 0
	global_load_dwordx4 v[72:75], v2, s[14:15]
	s_add_u32 s14, s14, 0x200000
	s_addc_u32 s15, s15, 0
	global_load_dwordx4 v[76:79], v2, s[14:15]
	s_add_u32 s14, s14, 0x200000
	s_addc_u32 s15, s15, 0
	global_load_dwordx4 v[80:83], v2, s[14:15]
	s_add_u32 s14, s14, 0x200000
	s_addc_u32 s15, s15, 0
	global_load_dwordx4 v[84:87], v2, s[14:15]
	s_add_u32 s14, s14, 0x200000
	s_addc_u32 s15, s15, 0
	global_load_dwordx4 v[88:91], v2, s[14:15]
	s_add_u32 s14, s14, 0x200000
	s_addc_u32 s15, s15, 0
	global_load_dwordx4 v[92:95], v2, s[14:15]
	s_add_u32 s14, s14, 0x200000
	s_addc_u32 s15, s15, 0
	global_load_dwordx4 v[96:99], v2, s[14:15]
	s_add_u32 s14, s14, 0x200000
	s_addc_u32 s15, s15, 0
	global_load_dwordx4 v[100:103], v2, s[14:15]
	s_add_u32 s14, s14, 0x200000
	s_addc_u32 s15, s15, 0
	global_load_dwordx4 v[104:107], v2, s[14:15]
	s_add_u32 s14, s14, 0x200000
	s_addc_u32 s15, s15, 0
	global_load_dwordx4 v[108:111], v2, s[14:15]
	s_add_u32 s14, s14, 0x200000
	s_addc_u32 s15, s15, 0
	global_load_dwordx4 v[112:115], v2, s[14:15]
	s_add_u32 s14, s14, 0x200000
	s_addc_u32 s15, s15, 0
	global_load_dwordx4 v[116:119], v2, s[14:15]
	s_add_u32 s14, s14, 0x200000
	s_addc_u32 s15, s15, 0
	global_load_dwordx4 v[120:123], v2, s[14:15]
	s_add_u32 s14, s14, 0x200000
	s_addc_u32 s15, s15, 0
	global_load_dwordx4 v[124:127], v2, s[14:15]
	s_add_u32 s14, s14, 0x200000
	s_addc_u32 s15, s15, 0
	s_waitcnt vmcnt(15)
	v_cvt_pk_bf16_f32 v64, v64, v65
	v_cvt_pk_bf16_f32 v65, v66, v67
	global_store_dwordx2 v3, v[64:65], s[24:25]
	s_add_u32 s24, s24, 0x100000
	s_addc_u32 s25, s25, 0
	global_load_dwordx4 v[64:67], v2, s[14:15]
	s_add_u32 s14, s14, 0x200000
	s_addc_u32 s15, s15, 0
	s_waitcnt vmcnt(16)
	v_cvt_pk_bf16_f32 v68, v68, v69
	v_cvt_pk_bf16_f32 v69, v70, v71
	global_store_dwordx2 v3, v[68:69], s[24:25]
	s_add_u32 s24, s24, 0x100000
	s_addc_u32 s25, s25, 0
	global_load_dwordx4 v[68:71], v2, s[14:15]
	s_add_u32 s14, s14, 0x200000
	s_addc_u32 s15, s15, 0
	s_waitcnt vmcnt(17)
	v_cvt_pk_bf16_f32 v72, v72, v73
	v_cvt_pk_bf16_f32 v73, v74, v75
	global_store_dwordx2 v3, v[72:73], s[24:25]
	s_add_u32 s24, s24, 0x100000
	s_addc_u32 s25, s25, 0
	global_load_dwordx4 v[72:75], v2, s[14:15]
	s_add_u32 s14, s14, 0x200000
	s_addc_u32 s15, s15, 0
	s_waitcnt vmcnt(18)
	v_cvt_pk_bf16_f32 v76, v76, v77
	v_cvt_pk_bf16_f32 v77, v78, v79
	global_store_dwordx2 v3, v[76:77], s[24:25]
	s_add_u32 s24, s24, 0x100000
	s_addc_u32 s25, s25, 0
	global_load_dwordx4 v[76:79], v2, s[14:15]
	s_add_u32 s14, s14, 0x200000
	s_addc_u32 s15, s15, 0
	s_waitcnt vmcnt(19)
	v_cvt_pk_bf16_f32 v80, v80, v81
	v_cvt_pk_bf16_f32 v81, v82, v83
	global_store_dwordx2 v3, v[80:81], s[24:25]
	s_add_u32 s24, s24, 0x100000
	s_addc_u32 s25, s25, 0
	global_load_dwordx4 v[80:83], v2, s[14:15]
	s_add_u32 s14, s14, 0x200000
	s_addc_u32 s15, s15, 0
	s_waitcnt vmcnt(20)
	v_cvt_pk_bf16_f32 v84, v84, v85
	v_cvt_pk_bf16_f32 v85, v86, v87
	global_store_dwordx2 v3, v[84:85], s[24:25]
	s_add_u32 s24, s24, 0x100000
	s_addc_u32 s25, s25, 0
	global_load_dwordx4 v[84:87], v2, s[14:15]
	s_add_u32 s14, s14, 0x200000
	s_addc_u32 s15, s15, 0
	s_waitcnt vmcnt(21)
	v_cvt_pk_bf16_f32 v88, v88, v89
	v_cvt_pk_bf16_f32 v89, v90, v91
	global_store_dwordx2 v3, v[88:89], s[24:25]
	s_add_u32 s24, s24, 0x100000
	s_addc_u32 s25, s25, 0
	global_load_dwordx4 v[88:91], v2, s[14:15]
	s_add_u32 s14, s14, 0x200000
	s_addc_u32 s15, s15, 0
	s_waitcnt vmcnt(22)
	v_cvt_pk_bf16_f32 v92, v92, v93
	v_cvt_pk_bf16_f32 v93, v94, v95
	global_store_dwordx2 v3, v[92:93], s[24:25]
	s_add_u32 s24, s24, 0x100000
	s_addc_u32 s25, s25, 0
	global_load_dwordx4 v[92:95], v2, s[14:15]
	s_add_u32 s14, s14, 0x200000
	s_addc_u32 s15, s15, 0
	s_waitcnt vmcnt(23)
	v_cvt_pk_bf16_f32 v96, v96, v97
	v_cvt_pk_bf16_f32 v97, v98, v99
	global_store_dwordx2 v3, v[96:97], s[24:25]
	s_add_u32 s24, s24, 0x100000
	s_addc_u32 s25, s25, 0
	global_load_dwordx4 v[96:99], v2, s[14:15]
	s_add_u32 s14, s14, 0x200000
	s_addc_u32 s15, s15, 0
	s_waitcnt vmcnt(24)
	v_cvt_pk_bf16_f32 v100, v100, v101
	v_cvt_pk_bf16_f32 v101, v102, v103
	global_store_dwordx2 v3, v[100:101], s[24:25]
	s_add_u32 s24, s24, 0x100000
	s_addc_u32 s25, s25, 0
	global_load_dwordx4 v[100:103], v2, s[14:15]
	s_add_u32 s14, s14, 0x200000
	s_addc_u32 s15, s15, 0
	s_waitcnt vmcnt(25)
	v_cvt_pk_bf16_f32 v104, v104, v105
	v_cvt_pk_bf16_f32 v105, v106, v107
	global_store_dwordx2 v3, v[104:105], s[24:25]
	s_add_u32 s24, s24, 0x100000
	s_addc_u32 s25, s25, 0
	global_load_dwordx4 v[104:107], v2, s[14:15]
	s_add_u32 s14, s14, 0x200000
	s_addc_u32 s15, s15, 0
	s_waitcnt vmcnt(26)
; __device__ __forceinline__ void cvt_rows(const float* __restrict__ src, bf16_t* __restrict__ dst, size_t n4, size_t gtid, size_t gn) {
;   for (size_t i0 = gtid; i0 < n4; i0 += 4 * gn) {
;     f32x4 v[4];
; #pragma unroll
;     for (int q = 0; q < 4; ++q) { const size_t i = i0 + q * gn; v[q] = i < n4 ? *(const f32x4*)(src + i * 4) : (f32x4){0.f, 0.f, 0.f, 0.f}; }
; #pragma unroll
;     for (int q = 0; q < 4; ++q) {
;       const size_t i = i0 + q * gn;
;       if (i < n4) { u32x2 w; w[0] = cvt_pk_bf16(v[q][0], v[q][1]); w[1] = cvt_pk_bf16(v[q][2], v[q][3]); *(u32x2*)(dst + i * 4) = w; }
;     }
;   }
; }
	v_cvt_pk_bf16_f32 v108, v108, v109
	v_cvt_pk_bf16_f32 v109, v110, v111
	global_store_dwordx2 v3, v[108:109], s[24:25]
	s_add_u32 s24, s24, 0x100000
	s_addc_u32 s25, s25, 0
	global_load_dwordx4 v[108:111], v2, s[14:15]
	s_add_u32 s14, s14, 0x200000
	s_addc_u32 s15, s15, 0
	s_waitcnt vmcnt(27)
	v_cvt_pk_bf16_f32 v112, v112, v113
	v_cvt_pk_bf16_f32 v113, v114, v115
	global_store_dwordx2 v3, v[112:113], s[24:25]
	s_add_u32 s24, s24, 0x100000
	s_addc_u32 s25, s25, 0
	global_load_dwordx4 v[112:115], v2, s[14:15]
	s_add_u32 s14, s14, 0x200000
	s_addc_u32 s15, s15, 0
	s_waitcnt vmcnt(28)
	v_cvt_pk_bf16_f32 v116, v116, v117
	v_cvt_pk_bf16_f32 v117, v118, v119
	global_store_dwordx2 v3, v[116:117], s[24:25]
	s_add_u32 s24, s24, 0x100000
	s_addc_u32 s25, s25, 0
	global_load_dwordx4 v[116:119], v2, s[14:15]
	s_add_u32 s14, s14, 0x200000
	s_addc_u32 s15, s15, 0
	s_waitcnt vmcnt(29)
	v_cvt_pk_bf16_f32 v120, v120, v121
	v_cvt_pk_bf16_f32 v121, v122, v123
	global_store_dwordx2 v3, v[120:121], s[24:25]
	s_add_u32 s24, s24, 0x100000
	s_addc_u32 s25, s25, 0
	global_load_dwordx4 v[120:123], v2, s[14:15]
	s_add_u32 s14, s14, 0x200000
	s_addc_u32 s15, s15, 0
	s_waitcnt vmcnt(30)
	v_cvt_pk_bf16_f32 v124, v124, v125
	v_cvt_pk_bf16_f32 v125, v126, v127
	global_store_dwordx2 v3, v[124:125], s[24:25]
	s_add_u32 s24, s24, 0x100000
	s_addc_u32 s25, s25, 0
	global_load_dwordx4 v[124:127], v2, s[14:15]
	s_add_u32 s14, s14, 0x200000
	s_addc_u32 s15, s15, 0
	s_waitcnt vmcnt(30)
	v_cvt_pk_bf16_f32 v64, v64, v65
	v_cvt_pk_bf16_f32 v65, v66, v67
	global_store_dwordx2 v3, v[64:65], s[24:25]
	s_add_u32 s24, s24, 0x100000
	s_addc_u32 s25, s25, 0
	global_load_dwordx4 v[64:67], v2, s[14:15]
	s_add_u32 s14, s14, 0x200000
	s_addc_u32 s15, s15, 0
	s_waitcnt vmcnt(30)
	v_cvt_pk_bf16_f32 v68, v68, v69
	v_cvt_pk_bf16_f32 v69, v70, v71
	global_store_dwordx2 v3, v[68:69], s[24:25]
	s_add_u32 s24, s24, 0x100000
	s_addc_u32 s25, s25, 0
	global_load_dwordx4 v[68:71], v2, s[14:15]
	s_add_u32 s14, s14, 0x200000
	s_addc_u32 s15, s15, 0
	s_waitcnt vmcnt(30)
	v_cvt_pk_bf16_f32 v72, v72, v73
	v_cvt_pk_bf16_f32 v73, v74, v75
	global_store_dwordx2 v3, v[72:73], s[24:25]
	s_add_u32 s24, s24, 0x100000
	s_addc_u32 s25, s25, 0
	global_load_dwordx4 v[72:75], v2, s[14:15]
	s_add_u32 s14, s14, 0x200000
	s_addc_u32 s15, s15, 0
	s_waitcnt vmcnt(30)
	v_cvt_pk_bf16_f32 v76, v76, v77
	v_cvt_pk_bf16_f32 v77, v78, v79
	global_store_dwordx2 v3, v[76:77], s[24:25]
	s_add_u32 s24, s24, 0x100000
	s_addc_u32 s25, s25, 0
	global_load_dwordx4 v[76:79], v2, s[14:15]
	s_add_u32 s14, s14, 0x200000
	s_addc_u32 s15, s15, 0
	s_waitcnt vmcnt(30)
	v_cvt_pk_bf16_f32 v80, v80, v81
	v_cvt_pk_bf16_f32 v81, v82, v83
	global_store_dwordx2 v3, v[80:81], s[24:25]
	s_add_u32 s24, s24, 0x100000
	s_addc_u32 s25, s25, 0
	global_load_dwordx4 v[80:83], v2, s[14:15]
	s_add_u32 s14, s14, 0x200000
	s_addc_u32 s15, s15, 0
	s_waitcnt vmcnt(30)
	v_cvt_pk_bf16_f32 v84, v84, v85
	v_cvt_pk_bf16_f32 v85, v86, v87
	global_store_dwordx2 v3, v[84:85], s[24:25]
	s_add_u32 s24, s24, 0x100000
	s_addc_u32 s25, s25, 0
	global_load_dwordx4 v[84:87], v2, s[14:15]
	s_add_u32 s14, s14, 0x200000
	s_addc_u32 s15, s15, 0
	s_waitcnt vmcnt(30)
	v_cvt_pk_bf16_f32 v88, v88, v89
	v_cvt_pk_bf16_f32 v89, v90, v91
	global_store_dwordx2 v3, v[88:89], s[24:25]
	s_add_u32 s24, s24, 0x100000
	s_addc_u32 s25, s25, 0
	global_load_dwordx4 v[88:91], v2, s[14:15]
	s_add_u32 s14, s14, 0x200000
	s_addc_u32 s15, s15, 0
	s_waitcnt vmcnt(30)
	v_cvt_pk_bf16_f32 v92, v92, v93
	v_cvt_pk_bf16_f32 v93, v94, v95
	global_store_dwordx2 v3, v[92:93], s[24:25]
	s_add_u32 s24, s24, 0x100000
	s_addc_u32 s25, s25, 0
	global_load_dwordx4 v[92:95], v2, s[14:15]
	s_add_u32 s14, s14, 0x200000
	s_addc_u32 s15, s15, 0
	s_waitcnt vmcnt(30)
	v_cvt_pk_bf16_f32 v96, v96, v97
	v_cvt_pk_bf16_f32 v97, v98, v99
	global_store_dwordx2 v3, v[96:97], s[24:25]
	s_add_u32 s24, s24, 0x100000
	s_addc_u32 s25, s25, 0
	global_load_dwordx4 v[96:99], v2, s[14:15]
	s_add_u32 s14, s14, 0x200000
	s_addc_u32 s15, s15, 0
	s_waitcnt vmcnt(30)
	v_cvt_pk_bf16_f32 v100, v100, v101
	v_cvt_pk_bf16_f32 v101, v102, v103
	global_store_dwordx2 v3, v[100:101], s[24:25]
	s_add_u32 s24, s24, 0x100000
	s_addc_u32 s25, s25, 0
	global_load_dwordx4 v[100:103], v2, s[14:15]
	s_add_u32 s14, s14, 0x200000
	s_addc_u32 s15, s15, 0
	s_waitcnt vmcnt(30)
	v_cvt_pk_bf16_f32 v104, v104, v105
	v_cvt_pk_bf16_f32 v105, v106, v107
	global_store_dwordx2 v3, v[104:105], s[24:25]
	s_add_u32 s24, s24, 0x100000
	s_addc_u32 s25, s25, 0
	global_load_dwordx4 v[104:107], v2, s[14:15]
	s_add_u32 s14, s14, 0x200000
	s_addc_u32 s15, s15, 0
	s_waitcnt vmcnt(30)
	v_cvt_pk_bf16_f32 v108, v108, v109
	v_cvt_pk_bf16_f32 v109, v110, v111
	global_store_dwordx2 v3, v[108:109], s[24:25]
	s_add_u32 s24, s24, 0x100000
	s_addc_u32 s25, s25, 0
	global_load_dwordx4 v[108:111], v2, s[14:15]
	s_add_u32 s14, s14, 0x200000
	s_addc_u32 s15, s15, 0
	s_waitcnt vmcnt(30)
	v_cvt_pk_bf16_f32 v112, v112, v113
	v_cvt_pk_bf16_f32 v113, v114, v115
	global_store_dwordx2 v3, v[112:113], s[24:25]
	s_add_u32 s24, s24, 0x100000
	s_addc_u32 s25, s25, 0
	global_load_dwordx4 v[112:115], v2, s[14:15]
	s_add_u32 s14, s14, 0x200000
	s_addc_u32 s15, s15, 0
	s_waitcnt vmcnt(30)
	v_cvt_pk_bf16_f32 v116, v116, v117
	v_cvt_pk_bf16_f32 v117, v118, v119
	global_store_dwordx2 v3, v[116:117], s[24:25]
	s_add_u32 s24, s24, 0x100000
	s_addc_u32 s25, s25, 0
	global_load_dwordx4 v[116:119], v2, s[14:15]
	s_add_u32 s14, s14, 0x200000
	s_addc_u32 s15, s15, 0
	s_waitcnt vmcnt(30)
; __device__ __forceinline__ void cvt_rows(const float* __restrict__ src, bf16_t* __restrict__ dst, size_t n4, size_t gtid, size_t gn) {
;   for (size_t i0 = gtid; i0 < n4; i0 += 4 * gn) {
;     f32x4 v[4];
; #pragma unroll
;     for (int q = 0; q < 4; ++q) { const size_t i = i0 + q * gn; v[q] = i < n4 ? *(const f32x4*)(src + i * 4) : (f32x4){0.f, 0.f, 0.f, 0.f}; }
; #pragma unroll
;     for (int q = 0; q < 4; ++q) {
;       const size_t i = i0 + q * gn;
;       if (i < n4) { u32x2 w; w[0] = cvt_pk_bf16(v[q][0], v[q][1]); w[1] = cvt_pk_bf16(v[q][2], v[q][3]); *(u32x2*)(dst + i * 4) = w; }
;     }
;   }
; }
	v_cvt_pk_bf16_f32 v120, v120, v121
	v_cvt_pk_bf16_f32 v121, v122, v123
	global_store_dwordx2 v3, v[120:121], s[24:25]
	s_add_u32 s24, s24, 0x100000
	s_addc_u32 s25, s25, 0
	global_load_dwordx4 v[120:123], v2, s[14:15]
	s_add_u32 s14, s14, 0x200000
	s_addc_u32 s15, s15, 0
	s_waitcnt vmcnt(30)
	v_cvt_pk_bf16_f32 v124, v124, v125
	v_cvt_pk_bf16_f32 v125, v126, v127
	global_store_dwordx2 v3, v[124:125], s[24:25]
	s_add_u32 s24, s24, 0x100000
	s_addc_u32 s25, s25, 0
	global_load_dwordx4 v[124:127], v2, s[14:15]
	s_add_u32 s14, s14, 0x200000
	s_addc_u32 s15, s15, 0
	s_waitcnt vmcnt(30)
	v_cvt_pk_bf16_f32 v64, v64, v65
	v_cvt_pk_bf16_f32 v65, v66, v67
	global_store_dwordx2 v3, v[64:65], s[24:25]
	s_add_u32 s24, s24, 0x100000
	s_addc_u32 s25, s25, 0
	global_load_dwordx4 v[64:67], v2, s[14:15]
	s_add_u32 s14, s14, 0x200000
	s_addc_u32 s15, s15, 0
	s_waitcnt vmcnt(30)
	v_cvt_pk_bf16_f32 v68, v68, v69
	v_cvt_pk_bf16_f32 v69, v70, v71
	global_store_dwordx2 v3, v[68:69], s[24:25]
	s_add_u32 s24, s24, 0x100000
	s_addc_u32 s25, s25, 0
	global_load_dwordx4 v[68:71], v2, s[14:15]
	s_add_u32 s14, s14, 0x200000
	s_addc_u32 s15, s15, 0
	s_waitcnt vmcnt(30)
	v_cvt_pk_bf16_f32 v72, v72, v73
	v_cvt_pk_bf16_f32 v73, v74, v75
	global_store_dwordx2 v3, v[72:73], s[24:25]
	s_add_u32 s24, s24, 0x100000
	s_addc_u32 s25, s25, 0
	global_load_dwordx4 v[72:75], v2, s[14:15]
	s_add_u32 s14, s14, 0x200000
	s_addc_u32 s15, s15, 0
	s_waitcnt vmcnt(30)
	v_cvt_pk_bf16_f32 v76, v76, v77
	v_cvt_pk_bf16_f32 v77, v78, v79
	global_store_dwordx2 v3, v[76:77], s[24:25]
	s_add_u32 s24, s24, 0x100000
	s_addc_u32 s25, s25, 0
	global_load_dwordx4 v[76:79], v2, s[14:15]
	s_add_u32 s14, s14, 0x200000
	s_addc_u32 s15, s15, 0
	s_waitcnt vmcnt(30)
	v_cvt_pk_bf16_f32 v80, v80, v81
	v_cvt_pk_bf16_f32 v81, v82, v83
	global_store_dwordx2 v3, v[80:81], s[24:25]
	s_add_u32 s24, s24, 0x100000
	s_addc_u32 s25, s25, 0
	global_load_dwordx4 v[80:83], v2, s[14:15]
	s_add_u32 s14, s14, 0x200000
	s_addc_u32 s15, s15, 0
	s_waitcnt vmcnt(30)
	v_cvt_pk_bf16_f32 v84, v84, v85
	v_cvt_pk_bf16_f32 v85, v86, v87
	global_store_dwordx2 v3, v[84:85], s[24:25]
	s_add_u32 s24, s24, 0x100000
	s_addc_u32 s25, s25, 0
	global_load_dwordx4 v[84:87], v2, s[14:15]
	s_add_u32 s14, s14, 0x200000
	s_addc_u32 s15, s15, 0
	s_waitcnt vmcnt(30)
	v_cvt_pk_bf16_f32 v88, v88, v89
	v_cvt_pk_bf16_f32 v89, v90, v91
	global_store_dwordx2 v3, v[88:89], s[24:25]
	s_add_u32 s24, s24, 0x100000
	s_addc_u32 s25, s25, 0
	global_load_dwordx4 v[88:91], v2, s[14:15]
	s_add_u32 s14, s14, 0x200000
	s_addc_u32 s15, s15, 0
	s_waitcnt vmcnt(30)
	v_cvt_pk_bf16_f32 v92, v92, v93
	v_cvt_pk_bf16_f32 v93, v94, v95
	global_store_dwordx2 v3, v[92:93], s[24:25]
	s_add_u32 s24, s24, 0x100000
	s_addc_u32 s25, s25, 0
	global_load_dwordx4 v[92:95], v2, s[14:15]
	s_add_u32 s14, s14, 0x200000
	s_addc_u32 s15, s15, 0
	s_waitcnt vmcnt(30)
	v_cvt_pk_bf16_f32 v96, v96, v97
	v_cvt_pk_bf16_f32 v97, v98, v99
	global_store_dwordx2 v3, v[96:97], s[24:25]
	s_add_u32 s24, s24, 0x100000
	s_addc_u32 s25, s25, 0
	global_load_dwordx4 v[96:99], v2, s[14:15]
	s_add_u32 s14, s14, 0x200000
	s_addc_u32 s15, s15, 0
	s_waitcnt vmcnt(30)
	v_cvt_pk_bf16_f32 v100, v100, v101
	v_cvt_pk_bf16_f32 v101, v102, v103
	global_store_dwordx2 v3, v[100:101], s[24:25]
	s_add_u32 s24, s24, 0x100000
	s_addc_u32 s25, s25, 0
	global_load_dwordx4 v[100:103], v2, s[14:15]
	s_add_u32 s14, s14, 0x200000
	s_addc_u32 s15, s15, 0
	s_waitcnt vmcnt(30)
	v_cvt_pk_bf16_f32 v104, v104, v105
	v_cvt_pk_bf16_f32 v105, v106, v107
	global_store_dwordx2 v3, v[104:105], s[24:25]
	s_add_u32 s24, s24, 0x100000
	s_addc_u32 s25, s25, 0
	global_load_dwordx4 v[104:107], v2, s[14:15]
	s_add_u32 s14, s14, 0x200000
	s_addc_u32 s15, s15, 0
	s_waitcnt vmcnt(30)
	v_cvt_pk_bf16_f32 v108, v108, v109
	v_cvt_pk_bf16_f32 v109, v110, v111
	global_store_dwordx2 v3, v[108:109], s[24:25]
	s_add_u32 s24, s24, 0x100000
	s_addc_u32 s25, s25, 0
	global_load_dwordx4 v[108:111], v2, s[14:15]
	s_add_u32 s14, s14, 0x200000
	s_addc_u32 s15, s15, 0
	s_waitcnt vmcnt(30)
	v_cvt_pk_bf16_f32 v112, v112, v113
	v_cvt_pk_bf16_f32 v113, v114, v115
	global_store_dwordx2 v3, v[112:113], s[24:25]
	s_add_u32 s24, s24, 0x100000
	s_addc_u32 s25, s25, 0
	global_load_dwordx4 v[112:115], v2, s[14:15]
	s_add_u32 s14, s14, 0x200000
	s_addc_u32 s15, s15, 0
	s_waitcnt vmcnt(30)
	v_cvt_pk_bf16_f32 v116, v116, v117
	v_cvt_pk_bf16_f32 v117, v118, v119
	global_store_dwordx2 v3, v[116:117], s[24:25]
	s_add_u32 s24, s24, 0x100000
	s_addc_u32 s25, s25, 0
	global_load_dwordx4 v[116:119], v2, s[14:15]
	s_add_u32 s14, s14, 0x200000
	s_addc_u32 s15, s15, 0
	s_waitcnt vmcnt(30)
; __device__ __forceinline__ void cvt_rows(const float* __restrict__ src, bf16_t* __restrict__ dst, size_t n4, size_t gtid, size_t gn) {
;   for (size_t i0 = gtid; i0 < n4; i0 += 4 * gn) {
;     f32x4 v[4];
; #pragma unroll
;     for (int q = 0; q < 4; ++q) { const size_t i = i0 + q * gn; v[q] = i < n4 ? *(const f32x4*)(src + i * 4) : (f32x4){0.f, 0.f, 0.f, 0.f}; }
; #pragma unroll
;     for (int q = 0; q < 4; ++q) {
;       const size_t i = i0 + q * gn;
;       if (i < n4) { u32x2 w; w[0] = cvt_pk_bf16(v[q][0], v[q][1]); w[1] = cvt_pk_bf16(v[q][2], v[q][3]); *(u32x2*)(dst + i * 4) = w; }
;     }
;   }
; }
	v_cvt_pk_bf16_f32 v120, v120, v121
	v_cvt_pk_bf16_f32 v121, v122, v123
	global_store_dwordx2 v3, v[120:121], s[24:25]
	s_add_u32 s24, s24, 0x100000
	s_addc_u32 s25, s25, 0
	global_load_dwordx4 v[120:123], v2, s[14:15]
	s_add_u32 s14, s14, 0x200000
	s_addc_u32 s15, s15, 0
	s_waitcnt vmcnt(30)
	v_cvt_pk_bf16_f32 v124, v124, v125
	v_cvt_pk_bf16_f32 v125, v126, v127
	global_store_dwordx2 v3, v[124:125], s[24:25]
	s_add_u32 s24, s24, 0x100000
	s_addc_u32 s25, s25, 0
	global_load_dwordx4 v[124:127], v2, s[14:15]
	s_add_u32 s14, s14, 0x200000
	s_addc_u32 s15, s15, 0
	s_waitcnt vmcnt(30)
	v_cvt_pk_bf16_f32 v64, v64, v65
	v_cvt_pk_bf16_f32 v65, v66, v67
	global_store_dwordx2 v3, v[64:65], s[24:25]
	s_add_u32 s24, s24, 0x100000
	s_addc_u32 s25, s25, 0
	s_waitcnt vmcnt(29)
	v_cvt_pk_bf16_f32 v68, v68, v69
	v_cvt_pk_bf16_f32 v69, v70, v71
	global_store_dwordx2 v3, v[68:69], s[24:25]
	s_add_u32 s24, s24, 0x100000
	s_addc_u32 s25, s25, 0
	s_waitcnt vmcnt(28)
	v_cvt_pk_bf16_f32 v72, v72, v73
	v_cvt_pk_bf16_f32 v73, v74, v75
	global_store_dwordx2 v3, v[72:73], s[24:25]
	s_add_u32 s24, s24, 0x100000
	s_addc_u32 s25, s25, 0
	s_waitcnt vmcnt(27)
	v_cvt_pk_bf16_f32 v76, v76, v77
	v_cvt_pk_bf16_f32 v77, v78, v79
	global_store_dwordx2 v3, v[76:77], s[24:25]
	s_add_u32 s24, s24, 0x100000
	s_addc_u32 s25, s25, 0
	s_waitcnt vmcnt(26)
	v_cvt_pk_bf16_f32 v80, v80, v81
	v_cvt_pk_bf16_f32 v81, v82, v83
	global_store_dwordx2 v3, v[80:81], s[24:25]
	s_add_u32 s24, s24, 0x100000
	s_addc_u32 s25, s25, 0
	s_waitcnt vmcnt(25)
	v_cvt_pk_bf16_f32 v84, v84, v85
	v_cvt_pk_bf16_f32 v85, v86, v87
	global_store_dwordx2 v3, v[84:85], s[24:25]
	s_add_u32 s24, s24, 0x100000
	s_addc_u32 s25, s25, 0
	s_waitcnt vmcnt(24)
	v_cvt_pk_bf16_f32 v88, v88, v89
	v_cvt_pk_bf16_f32 v89, v90, v91
	global_store_dwordx2 v3, v[88:89], s[24:25]
	s_add_u32 s24, s24, 0x100000
	s_addc_u32 s25, s25, 0
	s_waitcnt vmcnt(23)
	v_cvt_pk_bf16_f32 v92, v92, v93
	v_cvt_pk_bf16_f32 v93, v94, v95
	global_store_dwordx2 v3, v[92:93], s[24:25]
	s_add_u32 s24, s24, 0x100000
	s_addc_u32 s25, s25, 0
	s_waitcnt vmcnt(22)
	v_cvt_pk_bf16_f32 v96, v96, v97
	v_cvt_pk_bf16_f32 v97, v98, v99
	global_store_dwordx2 v3, v[96:97], s[24:25]
	s_add_u32 s24, s24, 0x100000
	s_addc_u32 s25, s25, 0
	s_waitcnt vmcnt(21)
	v_cvt_pk_bf16_f32 v100, v100, v101
	v_cvt_pk_bf16_f32 v101, v102, v103
	global_store_dwordx2 v3, v[100:101], s[24:25]
	s_add_u32 s24, s24, 0x100000
	s_addc_u32 s25, s25, 0
	s_waitcnt vmcnt(20)
	v_cvt_pk_bf16_f32 v104, v104, v105
	v_cvt_pk_bf16_f32 v105, v106, v107
	global_store_dwordx2 v3, v[104:105], s[24:25]
	s_add_u32 s24, s24, 0x100000
	s_addc_u32 s25, s25, 0
	s_waitcnt vmcnt(19)
	v_cvt_pk_bf16_f32 v108, v108, v109
	v_cvt_pk_bf16_f32 v109, v110, v111
	global_store_dwordx2 v3, v[108:109], s[24:25]
	s_add_u32 s24, s24, 0x100000
	s_addc_u32 s25, s25, 0
	s_waitcnt vmcnt(18)
	v_cvt_pk_bf16_f32 v112, v112, v113
	v_cvt_pk_bf16_f32 v113, v114, v115
	global_store_dwordx2 v3, v[112:113], s[24:25]
	s_add_u32 s24, s24, 0x100000
	s_addc_u32 s25, s25, 0
	s_waitcnt vmcnt(17)
	v_cvt_pk_bf16_f32 v116, v116, v117
	v_cvt_pk_bf16_f32 v117, v118, v119
	global_store_dwordx2 v3, v[116:117], s[24:25]
	s_add_u32 s24, s24, 0x100000
	s_addc_u32 s25, s25, 0
	s_waitcnt vmcnt(16)
	v_cvt_pk_bf16_f32 v120, v120, v121
	v_cvt_pk_bf16_f32 v121, v122, v123
	global_store_dwordx2 v3, v[120:121], s[24:25]
	s_add_u32 s24, s24, 0x100000
	s_addc_u32 s25, s25, 0
	s_waitcnt vmcnt(15)
	v_cvt_pk_bf16_f32 v124, v124, v125
	v_cvt_pk_bf16_f32 v125, v126, v127
	global_store_dwordx2 v3, v[124:125], s[24:25]
	s_add_u32 s24, s24, 0x100000
	s_addc_u32 s25, s25, 0
	s_branch .LBB0_2235
.Lprepx_orig:
	s_load_dwordx2 s[14:15], s[20:21], 0x0
	v_readlane_b32 s2, v254, 6
	v_readlane_b32 s34, v254, 8
	v_readlane_b32 s3, v254, 7
	v_readlane_b32 s35, v254, 9
	s_lshl_b64 s[0:1], s[2:3], 12
	s_lshl_b64 s[16:17], s[34:35], 14
	s_lshl_b64 s[24:25], s[34:35], 10
	v_lshl_add_u64 v[2:3], v[34:35], 3, s[0:1]
	s_mov_b64 s[0:1], 0x39c0000
	s_waitcnt lgkmcnt(0)
	s_add_u32 s26, s14, s16
	v_lshl_add_u64 v[18:19], v[2:3], 0, s[0:1]
	s_addc_u32 s27, s15, s17
	s_lshl_b64 s[0:1], s[2:3], 13
	s_lshl_b64 s[28:29], s[34:35], 15
	v_lshl_add_u64 v[20:21], v[34:35], 4, s[0:1]
	s_add_u32 s0, s24, s6
	s_addc_u32 s1, s25, s7
	s_add_u32 s30, s14, s49
	s_addc_u32 s31, s15, s33
	v_lshl_add_u64 v[2:3], s[0:1], 0, v[34:35]
	s_add_u32 s0, s10, s6
	v_mov_b64_e32 v[4:5], 0x39c0000
	s_addc_u32 s1, s11, s7
	v_lshl_add_u64 v[22:23], v[2:3], 3, v[4:5]
	v_lshl_add_u64 v[2:3], s[0:1], 0, v[34:35]
	s_add_u32 s0, s6, s8
	s_addc_u32 s1, s7, s9
	v_lshl_add_u64 v[24:25], v[2:3], 3, v[4:5]
	v_lshl_add_u64 v[2:3], s[0:1], 0, v[34:35]
	s_lshl_b64 s[0:1], s[34:35], 13
	s_add_u32 s34, s14, s0
	v_lshl_add_u64 v[26:27], v[2:3], 3, v[4:5]
	s_addc_u32 s35, s15, s1
	s_mov_b64 s[36:37], 0
	s_mov_b64 s[38:39], 0x7fffff
	s_mov_b64 s[40:41], s[22:23]
	v_mov_b64_e32 v[14:15], v[36:37]
	s_branch .LBB0_2223
